# v057 + the first half of the layer-1 weight conversion runs on the workgroups that own only five gate-up units while the others finish their sixth (conversion loads are nt, so they no longer disturb t
# speedup vs baseline: 1.0358x; 1.0037x over previous
; #define LAS __attribute__((address_space(3)))
; __global__ void __launch_bounds__(512, 2) fwd_mega(Args a) {
;     ...
;     auto convert_items = [&](int LL, int lo, int hi, int w0, int nw_, size_t wd_off) __attribute__((always_inline)) {
;         LAS float* scr = (LAS float*)(lds + wave * 16384);
;         for (int it0 = lo + w0; it0 < hi; it0 += nw_) {
;             int it = it0;
;             if (it < 2688) { const int kb = it / 168, nb = it % 168; tr_item(INF(6) + (size_t)LL * D * INC, INC, WSP(WS_WIN), 1024, 0, 32 * nb, 64 * kb, 32 * nb, scr, lane); continue; } it -= 2688;
;             if (it < 512) { const int kb = it / 32, nb = it % 32; tr_item(INF(13) + (size_t)LL * D * D, D, WSP(WS_PAB), 1024, 0, 32 * nb, 64 * kb, 32 * nb, scr, lane); continue; } it -= 512;
;             if (it < 512) { const int kb = it / 32, nb = it % 32; tr_item(INF(12) + (size_t)LL * D * D, D, WSP(WS_PAB), 1024, 0, 1024 + 32 * nb, 64 * kb, 32 * nb, scr, lane); continue; } it -= 512;
;             if (it < 512) { const int kb = it / 32, nb = it % 32; tr_item(INF(14) + (size_t)LL * D * D, D, WSP(WS_WO2), 1024, 0, 32 * nb, 64 * kb, 32 * nb, scr, lane); continue; } it -= 512;
;             if (it < 1408) { const int kb = it / 88, nb = it % 88, n0 = 32 * nb; tr_item(INF(16) + (size_t)LL * D * FF, FF, WSP(WS_WGU), 1024, 0, (n0 >> 7) * 256 + (n0 & 127), 64 * kb, n0, scr, lane); continue; } it -= 1408;
;             if (it < 1408) { const int kb = it / 88, nb = it % 88, n0 = 32 * nb; tr_item(INF(17) + (size_t)LL * D * FF, FF, WSP(WS_WGU), 1024, 0, (n0 >> 7) * 256 + 128 + (n0 & 127), 64 * kb, n0, scr, lane); continue; } it -= 1408;
;             { const int kb = it / 32, nb = it % 32; tr_item(INF(20) + (size_t)LL * FF * D, D, WSP(wd_off), 2816, 0, 32 * nb, 64 * kb, 32 * nb, scr, lane); }
;         }
;     };
.LBB0_850:
	s_cmpk_lt_u32 s2, 0x80
	s_cbranch_scc1 .Lgc_skip
	v_writelane_b32 v250, s0, 0
	v_writelane_b32 v250, s1, 1
	v_writelane_b32 v250, s2, 2
	v_writelane_b32 v250, s3, 3
	v_writelane_b32 v250, s4, 4
	v_writelane_b32 v250, s5, 5
	v_writelane_b32 v250, s6, 6
	v_writelane_b32 v250, s7, 7
	v_writelane_b32 v250, s8, 8
	v_writelane_b32 v250, s9, 9
	v_writelane_b32 v250, s10, 10
	v_writelane_b32 v250, s11, 11
	v_writelane_b32 v250, s12, 12
	v_writelane_b32 v250, s13, 13
	v_writelane_b32 v250, s14, 14
	v_writelane_b32 v250, s15, 15
	v_writelane_b32 v250, s16, 16
	v_writelane_b32 v250, s17, 17
	v_writelane_b32 v250, s18, 18
	v_writelane_b32 v250, s19, 19
	v_writelane_b32 v250, s20, 20
	v_writelane_b32 v250, s21, 21
	v_writelane_b32 v250, s22, 22
	v_writelane_b32 v250, s23, 23
	v_writelane_b32 v250, s24, 24
	v_writelane_b32 v250, s25, 25
	v_writelane_b32 v250, s26, 26
	v_writelane_b32 v250, s27, 27
	v_writelane_b32 v250, s28, 28
	v_writelane_b32 v250, s29, 29
	v_writelane_b32 v250, s30, 30
	v_writelane_b32 v250, s31, 31
	v_writelane_b32 v250, s32, 32
	v_writelane_b32 v250, s33, 33
	v_writelane_b32 v250, s34, 34
	v_writelane_b32 v250, s35, 35
	v_writelane_b32 v250, s36, 36
	v_writelane_b32 v250, s37, 37
	v_writelane_b32 v250, s38, 38
	v_writelane_b32 v250, s39, 39
	v_writelane_b32 v250, s40, 40
	v_writelane_b32 v250, s41, 41
	v_writelane_b32 v250, s42, 42
	v_writelane_b32 v250, s43, 43
	v_writelane_b32 v250, s44, 44
	v_writelane_b32 v250, s45, 45
	v_writelane_b32 v250, s46, 46
	v_writelane_b32 v250, s47, 47
	v_writelane_b32 v250, s48, 48
	v_writelane_b32 v250, s49, 49
	v_writelane_b32 v250, s50, 50
	v_writelane_b32 v250, s51, 51
	v_writelane_b32 v250, s52, 52
	v_writelane_b32 v250, s53, 53
	v_writelane_b32 v250, s54, 54
	v_writelane_b32 v250, s55, 55
	v_writelane_b32 v250, s56, 56
	v_writelane_b32 v250, s57, 57
	v_writelane_b32 v250, s58, 58
	v_writelane_b32 v250, s59, 59
	v_writelane_b32 v250, s60, 60
	v_writelane_b32 v250, s61, 61
	v_writelane_b32 v250, s62, 62
	v_writelane_b32 v250, s63, 63
	v_writelane_b32 v251, s64, 0
	v_writelane_b32 v251, s65, 1
	v_writelane_b32 v251, s66, 2
	v_writelane_b32 v251, s67, 3
	v_writelane_b32 v251, s68, 4
	v_writelane_b32 v251, s69, 5
	v_writelane_b32 v251, s70, 6
	v_writelane_b32 v251, s71, 7
	v_writelane_b32 v251, s72, 8
	v_writelane_b32 v251, s73, 9
	v_writelane_b32 v251, s74, 10
	v_writelane_b32 v251, s75, 11
	v_writelane_b32 v251, s76, 12
	v_writelane_b32 v251, s77, 13
	v_writelane_b32 v251, s78, 14
	v_writelane_b32 v251, s79, 15
	v_writelane_b32 v251, s80, 16
	v_writelane_b32 v251, s81, 17
	v_writelane_b32 v251, s82, 18
	v_writelane_b32 v251, s83, 19
	v_writelane_b32 v251, s84, 20
	v_writelane_b32 v251, s85, 21
	v_writelane_b32 v251, s86, 22
	v_writelane_b32 v251, s87, 23
	v_writelane_b32 v251, s88, 24
	v_writelane_b32 v251, s89, 25
	v_writelane_b32 v251, s90, 26
	v_writelane_b32 v251, s91, 27
	v_writelane_b32 v251, s92, 28
	v_writelane_b32 v251, s93, 29
	v_writelane_b32 v251, s94, 30
	v_writelane_b32 v251, s95, 31
	v_writelane_b32 v251, s96, 32
	v_writelane_b32 v251, s97, 33
	v_writelane_b32 v251, vcc_lo, 34
	v_writelane_b32 v251, vcc_hi, 35
	v_readlane_b32 s4, v247, 40
	v_readlane_b32 s5, v247, 41
	s_nop 4
	s_mov_b64 s[6:7], s[26:27]
	v_lshlrev_b32_e32 v2, 2, v205
	v_mul_u32_u24_e32 v6, 0x84, v200
	v_readlane_b32 s10, v246, 3
	v_mov_b32_e32 v3, 0
	v_mov_b32_e32 v7, v3
	v_add3_u32 v28, s10, v2, v6
	v_and_b32_e32 v6, 56, v204
	v_mul_u32_u24_e32 v8, 0x84, v6
	v_lshlrev_b32_e32 v6, 1, v6
	s_waitcnt lgkmcnt(0)
	v_lshl_add_u64 v[4:5], s[4:5], 0, v[2:3]
	v_lshl_add_u64 v[26:27], s[6:7], 0, v[6:7]
	s_mov_b64 s[4:5], 0xf600000
	v_lshl_add_u64 v[6:7], v[26:27], 0, s[4:5]
	v_readlane_b32 s4, v247, 32
	v_readlane_b32 s5, v247, 33
	v_readlane_b32 s6, v247, 34
	v_readlane_b32 s7, v247, 35
	s_nop 4
	v_lshlrev_b32_e32 v9, 2, v201
	s_mov_b64 s[8:9], 0xb00000
	v_add3_u32 v29, s10, v8, v9
	v_readlane_b32 s10, v247, 28
	v_readlane_b32 s11, v247, 29
	s_nop 4
	s_waitcnt lgkmcnt(0)
	v_lshl_add_u64 v[8:9], s[6:7], 0, v[2:3]
	s_mov_b64 s[6:7], 0x1a80000
	v_lshl_add_u64 v[12:13], s[4:5], 0, v[2:3]
	v_lshl_add_u64 v[4:5], v[4:5], 0, s[8:9]
	v_lshl_add_u64 v[8:9], v[8:9], 0, s[8:9]
	v_lshl_add_u64 v[10:11], v[26:27], 0, s[6:7]
	v_lshl_add_u64 v[12:13], v[12:13], 0, s[8:9]
	v_readlane_b32 s8, v247, 12
	v_readlane_b32 s9, v247, 13
	v_readlane_b32 s4, v247, 24
	v_readlane_b32 s5, v247, 25
	v_readlane_b32 s6, v247, 26
	v_readlane_b32 s7, v247, 27
	s_nop 4
	v_lshl_add_u64 v[14:15], s[10:11], 0, v[2:3]
	s_mov_b64 s[10:11], 0x400000
	s_mov_b64 s[12:13], 0x1680000
	s_waitcnt vmcnt(3) lgkmcnt(0)
	v_lshl_add_u64 v[24:25], s[8:9], 0, v[2:3]
	s_waitcnt vmcnt(1)
	v_lshl_add_u64 v[18:19], s[4:5], 0, v[2:3]
	s_mov_b64 s[4:5], 0x1280000
	v_lshl_add_u64 v[20:21], v[26:27], 0, s[4:5]
	s_mov_b64 s[4:5], 0x1500000
	v_lshl_add_u64 v[22:23], s[6:7], 0, v[2:3]
	v_lshl_add_u64 v[24:25], v[24:25], 0, s[4:5]
	s_mov_b64 s[4:5], 0x800000
	v_or_b32_e32 v30, 8, v201
	v_or_b32_e32 v31, 16, v201
	v_or_b32_e32 v32, 24, v201
	v_lshl_add_u64 v[14:15], v[14:15], 0, s[10:11]
	v_lshl_add_u64 v[16:17], v[26:27], 0, s[12:13]
	v_lshl_add_u64 v[18:19], v[18:19], 0, s[10:11]
	v_lshl_add_u64 v[22:23], v[22:23], 0, s[10:11]
	v_lshl_add_u64 v[26:27], v[26:27], 0, s[4:5]
	s_lshl_b32 s4, s22, 5
	s_lshl_b32 s5, s77, 5
	s_lshl_b32 s12, s22, 1
	s_lshl_b32 s13, s77, 1
	s_mov_b32 s7, 0
	s_movk_i32 s14, 0x7fff
	s_mov_b32 s15, 0xffff0000
	s_movk_i32 s16, 0x5000
	s_mov_b32 s17, 0xb000
	s_mov_b32 s18, 0x10000
	s_mov_b32 s19, 0x16000
	s_mov_b32 s20, 0x1b000
	s_mov_b32 s21, 0x21000
	s_mov_b32 s23, 0x26000
	s_mov_b32 s24, 0x2c000
	s_mov_b32 s25, 0x31000
	s_mov_b32 s28, 0x37000
	s_mov_b32 s29, 0x3c000
	s_mov_b32 s30, 0x42000
	s_mov_b32 s31, 0x47000
	s_mov_b32 s34, 0x4d000
	s_mov_b32 s35, 0x52000
	s_mov_b32 s36, 0x58000
	s_mov_b32 s37, 0x5d000
	s_mov_b32 s38, 0x63000
	s_mov_b32 s39, 0x68000
	s_mov_b32 s40, 0x6e000
	s_mov_b32 s41, 0x73000
	s_mov_b32 s42, 0x79000
	s_mov_b32 s43, 0x7e000
	s_mov_b32 s44, 0x84000
	s_mov_b32 s45, 0x89000
	s_mov_b32 s46, 0x8f000
	s_mov_b32 s47, 0x94000
	s_mov_b32 s48, 0x9a000
	s_mov_b32 s49, 0x9f000
	s_mov_b32 s50, 0xa5000
	s_mov_b32 s51, 0xaa000
	s_movk_i32 s52, 0x5400
	v_add_u32_e32 v33, 0x400, v28
	v_add_u32_e32 v34, 0x800, v28
	v_add_u32_e32 v35, 0xc00, v28
	v_add_u32_e32 v36, 0x1000, v28
	v_add_u32_e32 v37, 0x1400, v28
	v_add_u32_e32 v38, 0x1800, v28
	v_add_u32_e32 v39, 0x1c00, v28
	s_sub_i32 s53, s22, 0x400
	s_lshl_b32 s4, s53, 5
	s_lshl_b32 s12, s53, 1
	s_branch .Lgc_986
.Lgc_985:
	s_addk_i32 s53, 0x400
	s_lshl_b32 s4, s53, 5
	s_lshl_b32 s12, s53, 1
	s_cmpk_lt_i32 s53, 0x1080
	s_cbranch_scc0 .Lgc_exit

; #define LAS __attribute__((address_space(3)))
; __global__ void __launch_bounds__(512, 2) fwd_mega(Args a) {
;     ...
;     auto convert_items = [&](int LL, int lo, int hi, int w0, int nw_, size_t wd_off) __attribute__((always_inline)) {
;         LAS float* scr = (LAS float*)(lds + wave * 16384);
;         for (int it0 = lo + w0; it0 < hi; it0 += nw_) {
;             int it = it0;
;             if (it < 2688) { const int kb = it / 168, nb = it % 168; tr_item(INF(6) + (size_t)LL * D * INC, INC, WSP(WS_WIN), 1024, 0, 32 * nb, 64 * kb, 32 * nb, scr, lane); continue; } it -= 2688;
;             if (it < 512) { const int kb = it / 32, nb = it % 32; tr_item(INF(13) + (size_t)LL * D * D, D, WSP(WS_PAB), 1024, 0, 32 * nb, 64 * kb, 32 * nb, scr, lane); continue; } it -= 512;
;             if (it < 512) { const int kb = it / 32, nb = it % 32; tr_item(INF(12) + (size_t)LL * D * D, D, WSP(WS_PAB), 1024, 0, 1024 + 32 * nb, 64 * kb, 32 * nb, scr, lane); continue; } it -= 512;
;             if (it < 512) { const int kb = it / 32, nb = it % 32; tr_item(INF(14) + (size_t)LL * D * D, D, WSP(WS_WO2), 1024, 0, 32 * nb, 64 * kb, 32 * nb, scr, lane); continue; } it -= 512;
;             if (it < 1408) { const int kb = it / 88, nb = it % 88, n0 = 32 * nb; tr_item(INF(16) + (size_t)LL * D * FF, FF, WSP(WS_WGU), 1024, 0, (n0 >> 7) * 256 + (n0 & 127), 64 * kb, n0, scr, lane); continue; } it -= 1408;
;             if (it < 1408) { const int kb = it / 88, nb = it % 88, n0 = 32 * nb; tr_item(INF(17) + (size_t)LL * D * FF, FF, WSP(WS_WGU), 1024, 0, (n0 >> 7) * 256 + 128 + (n0 & 127), 64 * kb, n0, scr, lane); continue; } it -= 1408;
;             { const int kb = it / 32, nb = it % 32; tr_item(INF(20) + (size_t)LL * FF * D, D, WSP(wd_off), 2816, 0, 32 * nb, 64 * kb, 32 * nb, scr, lane); }
;         }
;     };
.Lgc_exit:
	v_readlane_b32 s0, v250, 0
	v_readlane_b32 s1, v250, 1
	v_readlane_b32 s2, v250, 2
	v_readlane_b32 s3, v250, 3
	v_readlane_b32 s4, v250, 4
	v_readlane_b32 s5, v250, 5
	v_readlane_b32 s6, v250, 6
	v_readlane_b32 s7, v250, 7
	v_readlane_b32 s8, v250, 8
	v_readlane_b32 s9, v250, 9
	v_readlane_b32 s10, v250, 10
	v_readlane_b32 s11, v250, 11
	v_readlane_b32 s12, v250, 12
	v_readlane_b32 s13, v250, 13
	v_readlane_b32 s14, v250, 14
	v_readlane_b32 s15, v250, 15
	v_readlane_b32 s16, v250, 16
	v_readlane_b32 s17, v250, 17
	v_readlane_b32 s18, v250, 18
	v_readlane_b32 s19, v250, 19
	v_readlane_b32 s20, v250, 20
	v_readlane_b32 s21, v250, 21
	v_readlane_b32 s22, v250, 22
	v_readlane_b32 s23, v250, 23
	v_readlane_b32 s24, v250, 24
	v_readlane_b32 s25, v250, 25
	v_readlane_b32 s26, v250, 26
	v_readlane_b32 s27, v250, 27
	v_readlane_b32 s28, v250, 28
	v_readlane_b32 s29, v250, 29
	v_readlane_b32 s30, v250, 30
	v_readlane_b32 s31, v250, 31
	v_readlane_b32 s32, v250, 32
	v_readlane_b32 s33, v250, 33
	v_readlane_b32 s34, v250, 34
	v_readlane_b32 s35, v250, 35
	v_readlane_b32 s36, v250, 36
	v_readlane_b32 s37, v250, 37
	v_readlane_b32 s38, v250, 38
	v_readlane_b32 s39, v250, 39
	v_readlane_b32 s40, v250, 40
	v_readlane_b32 s41, v250, 41
	v_readlane_b32 s42, v250, 42
	v_readlane_b32 s43, v250, 43
	v_readlane_b32 s44, v250, 44
	v_readlane_b32 s45, v250, 45
	v_readlane_b32 s46, v250, 46
	v_readlane_b32 s47, v250, 47
	v_readlane_b32 s48, v250, 48
	v_readlane_b32 s49, v250, 49
	v_readlane_b32 s50, v250, 50
	v_readlane_b32 s51, v250, 51
	v_readlane_b32 s52, v250, 52
	v_readlane_b32 s53, v250, 53
	v_readlane_b32 s54, v250, 54
	v_readlane_b32 s55, v250, 55
	v_readlane_b32 s56, v250, 56
	v_readlane_b32 s57, v250, 57
	v_readlane_b32 s58, v250, 58
	v_readlane_b32 s59, v250, 59
	v_readlane_b32 s60, v250, 60
	v_readlane_b32 s61, v250, 61
	v_readlane_b32 s62, v250, 62
	v_readlane_b32 s63, v250, 63
	v_readlane_b32 s64, v251, 0
	v_readlane_b32 s65, v251, 1
	v_readlane_b32 s66, v251, 2
	v_readlane_b32 s67, v251, 3
	v_readlane_b32 s68, v251, 4
	v_readlane_b32 s69, v251, 5
	v_readlane_b32 s70, v251, 6
	v_readlane_b32 s71, v251, 7
	v_readlane_b32 s72, v251, 8
	v_readlane_b32 s73, v251, 9
	v_readlane_b32 s74, v251, 10
	v_readlane_b32 s75, v251, 11
	v_readlane_b32 s76, v251, 12
	v_readlane_b32 s77, v251, 13
	v_readlane_b32 s78, v251, 14
	v_readlane_b32 s79, v251, 15
	v_readlane_b32 s80, v251, 16
	v_readlane_b32 s81, v251, 17
	v_readlane_b32 s82, v251, 18
	v_readlane_b32 s83, v251, 19
	v_readlane_b32 s84, v251, 20
	v_readlane_b32 s85, v251, 21
	v_readlane_b32 s86, v251, 22
	v_readlane_b32 s87, v251, 23
	v_readlane_b32 s88, v251, 24
	v_readlane_b32 s89, v251, 25
	v_readlane_b32 s90, v251, 26
	v_readlane_b32 s91, v251, 27
	v_readlane_b32 s92, v251, 28
	v_readlane_b32 s93, v251, 29
	v_readlane_b32 s94, v251, 30
	v_readlane_b32 s95, v251, 31
	v_readlane_b32 s96, v251, 32
	v_readlane_b32 s97, v251, 33
	v_readlane_b32 vcc_lo, v251, 34
	v_readlane_b32 vcc_hi, v251, 35
	s_nop 7

; #define LAS __attribute__((address_space(3)))
; __global__ void __launch_bounds__(512, 2) fwd_mega(Args a) {
;     ...
;     auto convert_items = [&](int LL, int lo, int hi, int w0, int nw_, size_t wd_off) __attribute__((always_inline)) {
;         LAS float* scr = (LAS float*)(lds + wave * 16384);
;         for (int it0 = lo + w0; it0 < hi; it0 += nw_) {
;             int it = it0;
;             if (it < 2688) { const int kb = it / 168, nb = it % 168; tr_item(INF(6) + (size_t)LL * D * INC, INC, WSP(WS_WIN), 1024, 0, 32 * nb, 64 * kb, 32 * nb, scr, lane); continue; } it -= 2688;
;             if (it < 512) { const int kb = it / 32, nb = it % 32; tr_item(INF(13) + (size_t)LL * D * D, D, WSP(WS_PAB), 1024, 0, 32 * nb, 64 * kb, 32 * nb, scr, lane); continue; } it -= 512;
;             if (it < 512) { const int kb = it / 32, nb = it % 32; tr_item(INF(12) + (size_t)LL * D * D, D, WSP(WS_PAB), 1024, 0, 1024 + 32 * nb, 64 * kb, 32 * nb, scr, lane); continue; } it -= 512;
;             if (it < 512) { const int kb = it / 32, nb = it % 32; tr_item(INF(14) + (size_t)LL * D * D, D, WSP(WS_WO2), 1024, 0, 32 * nb, 64 * kb, 32 * nb, scr, lane); continue; } it -= 512;
;             if (it < 1408) { const int kb = it / 88, nb = it % 88, n0 = 32 * nb; tr_item(INF(16) + (size_t)LL * D * FF, FF, WSP(WS_WGU), 1024, 0, (n0 >> 7) * 256 + (n0 & 127), 64 * kb, n0, scr, lane); continue; } it -= 1408;
;             if (it < 1408) { const int kb = it / 88, nb = it % 88, n0 = 32 * nb; tr_item(INF(17) + (size_t)LL * D * FF, FF, WSP(WS_WGU), 1024, 0, (n0 >> 7) * 256 + 128 + (n0 & 127), 64 * kb, n0, scr, lane); continue; } it -= 1408;
;             { const int kb = it / 32, nb = it % 32; tr_item(INF(20) + (size_t)LL * FF * D, D, WSP(wd_off), 2816, 0, 32 * nb, 64 * kb, 32 * nb, scr, lane); }
;         }
;     };
;     ...
;         if constexpr (l + 1 < NL) {
;             __syncthreads();
;             convert_items(l + 1, 0, 8448, gw, NGW, WS_WD1);
;             for (int it = gw; it < 160; it += NGW) sgu_wfrag_item(INF(10) + (size_t)(l + 1) * 8 * 128 * 128, (v4u*)(a.ws + WS_WF), it, lane);
.LBB0_983:
	v_readlane_b32 s4, v246, 4
	v_readlane_b32 s5, v246, 5
	s_andn2_b64 vcc, exec, s[4:5]
	s_barrier
	s_cbranch_vccnz .LBB0_1010
	v_readlane_b32 s4, v247, 40
	v_readlane_b32 s5, v247, 41
	s_nop 4
	s_mov_b64 s[6:7], s[26:27]
	v_lshlrev_b32_e32 v2, 2, v205
	v_mul_u32_u24_e32 v6, 0x84, v200
	v_readlane_b32 s10, v246, 3
	v_mov_b32_e32 v3, 0
	v_mov_b32_e32 v7, v3
	v_add3_u32 v28, s10, v2, v6
	v_and_b32_e32 v6, 56, v204
	v_mul_u32_u24_e32 v8, 0x84, v6
	v_lshlrev_b32_e32 v6, 1, v6
	s_waitcnt lgkmcnt(0)
	v_lshl_add_u64 v[4:5], s[4:5], 0, v[2:3]
	v_lshl_add_u64 v[26:27], s[6:7], 0, v[6:7]
	s_mov_b64 s[4:5], 0xf600000
	v_lshl_add_u64 v[6:7], v[26:27], 0, s[4:5]
	v_readlane_b32 s4, v247, 32
	v_readlane_b32 s5, v247, 33
	v_readlane_b32 s6, v247, 34
	v_readlane_b32 s7, v247, 35
	s_nop 4
	v_lshlrev_b32_e32 v9, 2, v201
	s_mov_b64 s[8:9], 0xb00000
	v_add3_u32 v29, s10, v8, v9
	v_readlane_b32 s10, v247, 28
	v_readlane_b32 s11, v247, 29
	s_nop 4
	s_waitcnt lgkmcnt(0)
	v_lshl_add_u64 v[8:9], s[6:7], 0, v[2:3]
	s_mov_b64 s[6:7], 0x1a80000
	v_lshl_add_u64 v[12:13], s[4:5], 0, v[2:3]
	v_lshl_add_u64 v[4:5], v[4:5], 0, s[8:9]
	v_lshl_add_u64 v[8:9], v[8:9], 0, s[8:9]
	v_lshl_add_u64 v[10:11], v[26:27], 0, s[6:7]
	v_lshl_add_u64 v[12:13], v[12:13], 0, s[8:9]
	v_readlane_b32 s8, v247, 12
	v_readlane_b32 s9, v247, 13
	v_readlane_b32 s4, v247, 24
	v_readlane_b32 s5, v247, 25
	v_readlane_b32 s6, v247, 26
	v_readlane_b32 s7, v247, 27
	s_nop 4
	v_lshl_add_u64 v[14:15], s[10:11], 0, v[2:3]
	s_mov_b64 s[10:11], 0x400000
	s_mov_b64 s[12:13], 0x1680000
	s_waitcnt vmcnt(3) lgkmcnt(0)
	v_lshl_add_u64 v[24:25], s[8:9], 0, v[2:3]
	s_waitcnt vmcnt(1)
	v_lshl_add_u64 v[18:19], s[4:5], 0, v[2:3]
	s_mov_b64 s[4:5], 0x1280000
	v_lshl_add_u64 v[20:21], v[26:27], 0, s[4:5]
	s_mov_b64 s[4:5], 0x1500000
	v_lshl_add_u64 v[22:23], s[6:7], 0, v[2:3]
	v_lshl_add_u64 v[24:25], v[24:25], 0, s[4:5]
	s_mov_b64 s[4:5], 0x800000
	v_or_b32_e32 v30, 8, v201
	v_or_b32_e32 v31, 16, v201
	v_or_b32_e32 v32, 24, v201
	v_lshl_add_u64 v[14:15], v[14:15], 0, s[10:11]
	v_lshl_add_u64 v[16:17], v[26:27], 0, s[12:13]
	v_lshl_add_u64 v[18:19], v[18:19], 0, s[10:11]
	v_lshl_add_u64 v[22:23], v[22:23], 0, s[10:11]
	v_lshl_add_u64 v[26:27], v[26:27], 0, s[4:5]
	s_lshl_b32 s4, s22, 5
	s_lshl_b32 s5, s77, 5
	s_lshl_b32 s12, s22, 1
	s_lshl_b32 s13, s77, 1
	s_mov_b32 s7, 0
	s_movk_i32 s14, 0x7fff
	s_mov_b32 s15, 0xffff0000
	s_movk_i32 s16, 0x5000
	s_mov_b32 s17, 0xb000
	s_mov_b32 s18, 0x10000
	s_mov_b32 s19, 0x16000
	s_mov_b32 s20, 0x1b000
	s_mov_b32 s21, 0x21000
	s_mov_b32 s23, 0x26000
	s_mov_b32 s24, 0x2c000
	s_mov_b32 s25, 0x31000
	s_mov_b32 s28, 0x37000
	s_mov_b32 s29, 0x3c000
	s_mov_b32 s30, 0x42000
	s_mov_b32 s31, 0x47000
	s_mov_b32 s34, 0x4d000
	s_mov_b32 s35, 0x52000
	s_mov_b32 s36, 0x58000
	s_mov_b32 s37, 0x5d000
	s_mov_b32 s38, 0x63000
	s_mov_b32 s39, 0x68000
	s_mov_b32 s40, 0x6e000
	s_mov_b32 s41, 0x73000
	s_mov_b32 s42, 0x79000
	s_mov_b32 s43, 0x7e000
	s_mov_b32 s44, 0x84000
	s_mov_b32 s45, 0x89000
	s_mov_b32 s46, 0x8f000
	s_mov_b32 s47, 0x94000
	s_mov_b32 s48, 0x9a000
	s_mov_b32 s49, 0x9f000
	s_mov_b32 s50, 0xa5000
	s_mov_b32 s51, 0xaa000
	s_movk_i32 s52, 0x5400
	v_add_u32_e32 v33, 0x400, v28
	v_add_u32_e32 v34, 0x800, v28
	v_add_u32_e32 v35, 0xc00, v28
	v_add_u32_e32 v36, 0x1000, v28
	v_add_u32_e32 v37, 0x1400, v28
	v_add_u32_e32 v38, 0x1800, v28
	v_add_u32_e32 v39, 0x1c00, v28
	s_mov_b32 s53, s22
	s_addk_i32 s53, 0x1080
	s_add_i32 s4, s4, 0x21000
	s_addk_i32 s12, 0x2100
	s_branch .LBB0_986
